# P1 epilogue: raw (no-silu) row-major tiles get a dedicated path instead of computing silu and discarding it
# speedup vs baseline: 1.0087x; 1.0087x over previous
; __device__ __forceinline__ unsigned pk2(float lo, float hi) { f32x2_t v = {lo, hi}; bf16x2_t b = __builtin_convertvector(v, bf16x2_t); return __builtin_bit_cast(unsigned, b); }
; __device__ __forceinline__ float fsigmoid(float x) { return __builtin_amdgcn_rcpf(1.f + fexp(-x)); }
;     ...
;       } else if (nw < INW) {
;         u16* dst; int ldd, c0; bool act;
;         if (nw < 2048) { dst = p.GA; ldd = 512; c0 = nw - 1536; act = true; }
;         else if (nw < 3712) { dst = p.PB; ldd = PBW; c0 = nw - 2048; act = false; }
;         else { dst = p.GB; ldd = 512; c0 = nw - 3712; act = true; }
; #pragma unroll
;         for (int tt = 0; tt < 4; ++tt) {
;           u16* srow = stg + (tt * 32 + l31) * LD;
; #pragma unroll
;           for (int ct = 0; ct < 2; ++ct)
; #pragma unroll
;             for (int rq = 0; rq < 4; ++rq) {
;               float v[4];
; #pragma unroll
;               for (int e = 0; e < 4; ++e) { v[e] = acc[ct][tt][rq * 4 + e] * rsv[tt]; if (act) v[e] = v[e] * fsigmoid(v[e]); }
;               u32x2 w; w.x = pk2(v[0], v[1]); w.y = pk2(v[2], v[3]);
;               *(u32x2*)(srow + ct * 32 + 8 * rq + 4 * h) = w;
.LBB0_145:
	s_andn2_b64 vcc, exec, s[36:37]
	s_cbranch_vccnz .Lp1_raw
	s_waitcnt vmcnt(3)
	v_mul_f32_e32 v7, v114, v10
	v_mul_f32_e32 v9, 0xbfb8aa3b, v7
	v_mul_f32_e32 v11, v115, v10
	v_exp_f32_e32 v9, v9
	v_mul_f32_e32 v13, 0xbfb8aa3b, v11
	v_exp_f32_e32 v13, v13
	v_mul_f32_e32 v14, v116, v10
	v_add_f32_e32 v9, 1.0, v9
	v_rcp_f32_e32 v9, v9
	v_add_f32_e32 v13, 1.0, v13
	v_mul_f32_e32 v15, 0xbfb8aa3b, v14
	v_rcp_f32_e32 v13, v13
	v_exp_f32_e32 v15, v15
	v_mul_f32_e32 v9, v7, v9
	v_cndmask_b32_e64 v7, v7, v9, s[36:37]
	v_mul_f32_e32 v9, v11, v13
	v_add_f32_e32 v13, 1.0, v15
	v_mul_f32_e32 v15, v117, v10
	v_mul_f32_e32 v16, 0xbfb8aa3b, v15
	v_rcp_f32_e32 v13, v13
	v_exp_f32_e32 v16, v16
	v_cndmask_b32_e64 v9, v11, v9, s[36:37]
	v_mul_u32_u24_e32 v2, 0x90, v225
	v_mul_f32_e32 v11, v14, v13
	v_add_f32_e32 v13, 1.0, v16
	v_mul_f32_e32 v16, v118, v10
	v_cndmask_b32_e64 v11, v14, v11, s[36:37]
	v_mul_f32_e32 v14, 0xbfb8aa3b, v16
	v_rcp_f32_e32 v13, v13
	v_exp_f32_e32 v17, v14
	v_cvt_pk_bf16_f32 v14, v7, v9
	v_mul_f32_e32 v9, v119, v10
	v_mul_f32_e32 v13, v15, v13
	v_add_f32_e32 v7, 1.0, v17
	v_cndmask_b32_e64 v13, v15, v13, s[36:37]
	v_rcp_f32_e32 v7, v7
	v_mul_f32_e32 v15, 0xbfb8aa3b, v9
	v_exp_f32_e32 v17, v15
	v_cvt_pk_bf16_f32 v15, v11, v13
	v_mul_f32_e32 v7, v16, v7
	v_mul_f32_e32 v13, v120, v10
	v_cndmask_b32_e64 v7, v16, v7, s[36:37]
	v_add_f32_e32 v11, 1.0, v17
	v_mul_f32_e32 v16, 0xbfb8aa3b, v13
	v_mul_f32_e32 v17, v121, v10
	v_exp_f32_e32 v16, v16
	v_mul_f32_e32 v146, 0xbfb8aa3b, v17
	v_exp_f32_e32 v146, v146
	v_rcp_f32_e32 v11, v11
	v_add_f32_e32 v16, 1.0, v16
	v_rcp_f32_e32 v16, v16
	v_add_f32_e32 v146, 1.0, v146
	v_rcp_f32_e32 v146, v146
	v_mul_f32_e32 v11, v9, v11
	v_cndmask_b32_e64 v9, v9, v11, s[36:37]
	v_mul_f32_e32 v11, v13, v16
	v_cndmask_b32_e64 v11, v13, v11, s[36:37]
	v_mul_f32_e32 v13, v17, v146
	v_cndmask_b32_e64 v13, v17, v13, s[36:37]
	v_cvt_pk_bf16_f32 v16, v7, v9
	v_mul_f32_e32 v7, v122, v10
	v_cvt_pk_bf16_f32 v17, v11, v13
	v_mul_f32_e32 v9, 0xbfb8aa3b, v7
	v_mul_f32_e32 v11, v123, v10
	v_exp_f32_e32 v9, v9
	v_mul_f32_e32 v13, 0xbfb8aa3b, v11
	v_exp_f32_e32 v13, v13
	v_add3_u32 v2, s7, v5, v2
	ds_write2_b64 v2, v[14:15], v[16:17] offset1:2
	v_add_f32_e32 v9, 1.0, v9
	v_mul_f32_e32 v14, v124, v10
	v_rcp_f32_e32 v9, v9
	v_add_f32_e32 v13, 1.0, v13
	v_mul_f32_e32 v15, 0xbfb8aa3b, v14
	v_rcp_f32_e32 v13, v13
	v_exp_f32_e32 v15, v15
	v_mul_f32_e32 v9, v7, v9
	v_cndmask_b32_e64 v7, v7, v9, s[36:37]
	v_mul_f32_e32 v9, v11, v13
	v_add_f32_e32 v13, 1.0, v15
	v_mul_f32_e32 v15, v125, v10
	v_mul_f32_e32 v16, 0xbfb8aa3b, v15
	v_rcp_f32_e32 v13, v13
	v_exp_f32_e32 v16, v16
	v_cndmask_b32_e64 v9, v11, v9, s[36:37]
	s_add_u32 s38, s0, s38
	v_mul_f32_e32 v11, v14, v13
	v_add_f32_e32 v13, 1.0, v16
	v_mul_f32_e32 v16, v126, v10
	v_cndmask_b32_e64 v11, v14, v11, s[36:37]
	v_mul_f32_e32 v14, 0xbfb8aa3b, v16
	v_rcp_f32_e32 v13, v13
	v_exp_f32_e32 v17, v14
	v_cvt_pk_bf16_f32 v14, v7, v9
	v_mul_f32_e32 v9, v127, v10
	v_mul_f32_e32 v13, v15, v13
	v_add_f32_e32 v7, 1.0, v17
	v_cndmask_b32_e64 v13, v15, v13, s[36:37]
	v_rcp_f32_e32 v7, v7
	v_mul_f32_e32 v15, 0xbfb8aa3b, v9
	v_exp_f32_e32 v17, v15
	v_cvt_pk_bf16_f32 v15, v11, v13
	v_mul_f32_e32 v7, v16, v7
	v_mul_f32_e32 v13, v128, v10
	v_cndmask_b32_e64 v7, v16, v7, s[36:37]
	v_add_f32_e32 v11, 1.0, v17
	v_mul_f32_e32 v16, 0xbfb8aa3b, v13
	v_mul_f32_e32 v17, v129, v10
	v_exp_f32_e32 v16, v16
	v_mul_f32_e32 v146, 0xbfb8aa3b, v17
	v_exp_f32_e32 v146, v146
	v_rcp_f32_e32 v11, v11
	v_add_f32_e32 v16, 1.0, v16
	v_rcp_f32_e32 v16, v16
	v_add_f32_e32 v146, 1.0, v146
	v_rcp_f32_e32 v146, v146
	v_mul_f32_e32 v11, v9, v11
	v_cndmask_b32_e64 v9, v9, v11, s[36:37]
	v_mul_f32_e32 v11, v13, v16
	v_cndmask_b32_e64 v11, v13, v11, s[36:37]
	v_mul_f32_e32 v13, v17, v146
	v_cndmask_b32_e64 v13, v17, v13, s[36:37]
	v_cvt_pk_bf16_f32 v16, v7, v9
	v_mul_f32_e32 v7, v130, v10
	v_cvt_pk_bf16_f32 v17, v11, v13
	v_mul_f32_e32 v9, 0xbfb8aa3b, v7
	v_mul_f32_e32 v11, v131, v10
	v_exp_f32_e32 v9, v9
	v_mul_f32_e32 v13, 0xbfb8aa3b, v11
	v_exp_f32_e32 v13, v13
	ds_write2_b64 v2, v[14:15], v[16:17] offset0:4 offset1:6
	v_add_f32_e32 v9, 1.0, v9
	v_mul_f32_e32 v14, v132, v10
	v_rcp_f32_e32 v9, v9
	v_add_f32_e32 v13, 1.0, v13
	v_mul_f32_e32 v15, 0xbfb8aa3b, v14
	v_rcp_f32_e32 v13, v13
	v_exp_f32_e32 v15, v15
	v_mul_f32_e32 v9, v7, v9
	v_cndmask_b32_e64 v7, v7, v9, s[36:37]
	v_mul_f32_e32 v9, v11, v13
	v_add_f32_e32 v13, 1.0, v15
	v_mul_f32_e32 v15, v133, v10
	v_mul_f32_e32 v16, 0xbfb8aa3b, v15
	v_rcp_f32_e32 v13, v13
	v_exp_f32_e32 v16, v16
	v_cndmask_b32_e64 v9, v11, v9, s[36:37]
	s_addc_u32 s39, s1, s39
	v_mul_f32_e32 v11, v14, v13
	v_add_f32_e32 v13, 1.0, v16
	v_mul_f32_e32 v16, v134, v10
	v_cndmask_b32_e64 v11, v14, v11, s[36:37]
	v_mul_f32_e32 v14, 0xbfb8aa3b, v16
	v_rcp_f32_e32 v13, v13
	v_exp_f32_e32 v17, v14
	v_cvt_pk_bf16_f32 v14, v7, v9
	v_mul_f32_e32 v9, v135, v10
	v_mul_f32_e32 v13, v15, v13
	v_add_f32_e32 v7, 1.0, v17
	v_cndmask_b32_e64 v13, v15, v13, s[36:37]
	v_rcp_f32_e32 v7, v7
	v_mul_f32_e32 v15, 0xbfb8aa3b, v9
	v_exp_f32_e32 v17, v15
	v_cvt_pk_bf16_f32 v15, v11, v13
	v_mul_f32_e32 v7, v16, v7
	v_mul_f32_e32 v13, v136, v10
	v_cndmask_b32_e64 v7, v16, v7, s[36:37]
	v_add_f32_e32 v11, 1.0, v17
	v_mul_f32_e32 v16, 0xbfb8aa3b, v13
	v_mul_f32_e32 v17, v137, v10
	v_exp_f32_e32 v16, v16
	v_mul_f32_e32 v146, 0xbfb8aa3b, v17
	v_exp_f32_e32 v146, v146
	v_rcp_f32_e32 v11, v11
	v_add_f32_e32 v16, 1.0, v16
	v_rcp_f32_e32 v16, v16
	v_add_f32_e32 v146, 1.0, v146
	v_rcp_f32_e32 v146, v146
	v_mul_f32_e32 v11, v9, v11
	v_cndmask_b32_e64 v9, v9, v11, s[36:37]
	v_mul_f32_e32 v11, v13, v16
	v_cndmask_b32_e64 v11, v13, v11, s[36:37]
; __device__ __forceinline__ unsigned pk2(float lo, float hi) { f32x2_t v = {lo, hi}; bf16x2_t b = __builtin_convertvector(v, bf16x2_t); return __builtin_bit_cast(unsigned, b); }
; __device__ __forceinline__ float fsigmoid(float x) { return __builtin_amdgcn_rcpf(1.f + fexp(-x)); }
;     ...
;         for (int tt = 0; tt < 4; ++tt) {
;           u16* srow = stg + (tt * 32 + l31) * LD;
; #pragma unroll
;           for (int ct = 0; ct < 2; ++ct)
; #pragma unroll
;             for (int rq = 0; rq < 4; ++rq) {
;               float v[4];
; #pragma unroll
;               for (int e = 0; e < 4; ++e) { v[e] = acc[ct][tt][rq * 4 + e] * rsv[tt]; if (act) v[e] = v[e] * fsigmoid(v[e]); }
;               u32x2 w; w.x = pk2(v[0], v[1]); w.y = pk2(v[2], v[3]);
;               *(u32x2*)(srow + ct * 32 + 8 * rq + 4 * h) = w;
	v_mul_f32_e32 v13, v17, v146
	v_cndmask_b32_e64 v13, v17, v13, s[36:37]
	v_cvt_pk_bf16_f32 v16, v7, v9
	v_mul_f32_e32 v7, v138, v10
	v_cvt_pk_bf16_f32 v17, v11, v13
	v_mul_f32_e32 v9, 0xbfb8aa3b, v7
	v_mul_f32_e32 v11, v139, v10
	v_exp_f32_e32 v9, v9
	v_mul_f32_e32 v13, 0xbfb8aa3b, v11
	v_exp_f32_e32 v13, v13
	ds_write2_b64 v2, v[14:15], v[16:17] offset0:8 offset1:10
	v_add_f32_e32 v9, 1.0, v9
	v_mul_f32_e32 v14, v140, v10
	v_rcp_f32_e32 v9, v9
	v_add_f32_e32 v13, 1.0, v13
	v_mul_f32_e32 v15, 0xbfb8aa3b, v14
	v_rcp_f32_e32 v13, v13
	v_exp_f32_e32 v15, v15
	v_mul_f32_e32 v9, v7, v9
	v_cndmask_b32_e64 v7, v7, v9, s[36:37]
	v_mul_f32_e32 v9, v11, v13
	v_add_f32_e32 v13, 1.0, v15
	v_mul_f32_e32 v15, v141, v10
	v_mul_f32_e32 v16, 0xbfb8aa3b, v15
	v_rcp_f32_e32 v13, v13
	v_exp_f32_e32 v16, v16
	v_cndmask_b32_e64 v9, v11, v9, s[36:37]
	s_load_dwordx2 s[38:39], s[38:39], 0x0
	v_mul_f32_e32 v11, v14, v13
	v_add_f32_e32 v13, 1.0, v16
	v_mul_f32_e32 v16, v142, v10
	v_cndmask_b32_e64 v11, v14, v11, s[36:37]
	v_mul_f32_e32 v14, 0xbfb8aa3b, v16
	v_rcp_f32_e32 v13, v13
	v_exp_f32_e32 v17, v14
	v_cvt_pk_bf16_f32 v14, v7, v9
	v_mul_f32_e32 v9, v143, v10
	v_mul_f32_e32 v13, v15, v13
	v_add_f32_e32 v7, 1.0, v17
	v_cndmask_b32_e64 v13, v15, v13, s[36:37]
	v_rcp_f32_e32 v7, v7
	v_mul_f32_e32 v15, 0xbfb8aa3b, v9
	v_exp_f32_e32 v17, v15
	v_cvt_pk_bf16_f32 v15, v11, v13
	v_mul_f32_e32 v7, v16, v7
	v_mul_f32_e32 v13, v144, v10
	v_cndmask_b32_e64 v7, v16, v7, s[36:37]
	v_add_f32_e32 v11, 1.0, v17
	v_mul_f32_e32 v16, 0xbfb8aa3b, v13
	v_mul_f32_e32 v17, v145, v10
	v_exp_f32_e32 v16, v16
	v_mul_f32_e32 v146, 0xbfb8aa3b, v17
	v_exp_f32_e32 v146, v146
	v_rcp_f32_e32 v11, v11
	v_add_f32_e32 v16, 1.0, v16
	v_rcp_f32_e32 v16, v16
	v_add_f32_e32 v146, 1.0, v146
	v_rcp_f32_e32 v146, v146
	v_mul_f32_e32 v11, v9, v11
	v_cndmask_b32_e64 v9, v9, v11, s[36:37]
	v_mul_f32_e32 v11, v13, v16
	v_cndmask_b32_e64 v11, v13, v11, s[36:37]
	v_mul_f32_e32 v13, v17, v146
	v_cndmask_b32_e64 v13, v17, v13, s[36:37]
	v_cvt_pk_bf16_f32 v16, v7, v9
	s_waitcnt vmcnt(2)
	v_mul_f32_e32 v7, v82, v8
	v_cvt_pk_bf16_f32 v17, v11, v13
	v_mul_f32_e32 v9, 0xbfb8aa3b, v7
	v_mul_f32_e32 v11, v83, v8
	v_exp_f32_e32 v9, v9
	v_mul_f32_e32 v13, 0xbfb8aa3b, v11
	v_exp_f32_e32 v13, v13
	ds_write2_b64 v2, v[14:15], v[16:17] offset0:12 offset1:14
	v_add_f32_e32 v9, 1.0, v9
	v_mul_f32_e32 v14, v84, v8
	v_rcp_f32_e32 v9, v9
	v_add_f32_e32 v13, 1.0, v13
	v_mul_f32_e32 v15, 0xbfb8aa3b, v14
	v_rcp_f32_e32 v13, v13
	v_exp_f32_e32 v15, v15
	v_mul_f32_e32 v9, v7, v9
	v_cndmask_b32_e64 v7, v7, v9, s[36:37]
	v_mul_f32_e32 v9, v11, v13
	v_add_f32_e32 v13, 1.0, v15
	v_mul_f32_e32 v15, v85, v8
	v_mul_f32_e32 v16, 0xbfb8aa3b, v15
	v_rcp_f32_e32 v13, v13
	v_exp_f32_e32 v16, v16
	v_cndmask_b32_e64 v9, v11, v9, s[36:37]
	s_add_i32 s20, s35, s64
	v_mul_f32_e32 v11, v14, v13
	v_add_f32_e32 v13, 1.0, v16
	v_mul_f32_e32 v16, v86, v8
	v_cndmask_b32_e64 v11, v14, v11, s[36:37]
	v_mul_f32_e32 v14, 0xbfb8aa3b, v16
	v_rcp_f32_e32 v13, v13
	v_exp_f32_e32 v17, v14
	v_cvt_pk_bf16_f32 v14, v7, v9
	v_mul_f32_e32 v9, v87, v8
	v_mul_f32_e32 v13, v15, v13
	v_add_f32_e32 v7, 1.0, v17
	v_cndmask_b32_e64 v13, v15, v13, s[36:37]
	v_rcp_f32_e32 v7, v7
	v_mul_f32_e32 v15, 0xbfb8aa3b, v9
	v_exp_f32_e32 v17, v15
	v_cvt_pk_bf16_f32 v15, v11, v13
	v_mul_f32_e32 v7, v16, v7
	v_mul_f32_e32 v13, v88, v8
	v_cndmask_b32_e64 v7, v16, v7, s[36:37]
	v_add_f32_e32 v11, 1.0, v17
	v_mul_f32_e32 v16, 0xbfb8aa3b, v13
	v_mul_f32_e32 v17, v89, v8
	v_exp_f32_e32 v16, v16
	v_mul_f32_e32 v146, 0xbfb8aa3b, v17
	v_exp_f32_e32 v146, v146
	v_rcp_f32_e32 v11, v11
	v_add_f32_e32 v16, 1.0, v16
	v_rcp_f32_e32 v16, v16
	v_add_f32_e32 v146, 1.0, v146
	v_rcp_f32_e32 v146, v146
	v_mul_f32_e32 v11, v9, v11
	v_cndmask_b32_e64 v9, v9, v11, s[36:37]
	v_mul_f32_e32 v11, v13, v16
	v_cndmask_b32_e64 v11, v13, v11, s[36:37]
	v_mul_f32_e32 v13, v17, v146
	v_cndmask_b32_e64 v13, v17, v13, s[36:37]
	v_cvt_pk_bf16_f32 v16, v7, v9
	v_mul_f32_e32 v9, v90, v8
	v_cvt_pk_bf16_f32 v17, v11, v13
	v_mul_f32_e32 v11, 0xbfb8aa3b, v9
	v_mul_f32_e32 v13, v91, v8
	v_exp_f32_e32 v11, v11
	v_mul_f32_e32 v146, 0xbfb8aa3b, v13
	v_exp_f32_e32 v146, v146
	v_add_u32_e32 v7, 0x1000, v2
	ds_write2_b64 v7, v[14:15], v[16:17] offset0:64 offset1:66
	v_add_f32_e32 v11, 1.0, v11
	v_mul_f32_e32 v15, v92, v8
	v_rcp_f32_e32 v11, v11
	v_add_f32_e32 v14, 1.0, v146
	v_mul_f32_e32 v16, 0xbfb8aa3b, v15
	v_rcp_f32_e32 v14, v14
	v_exp_f32_e32 v16, v16
	v_mul_f32_e32 v11, v9, v11
	v_cndmask_b32_e64 v9, v9, v11, s[36:37]
	v_mul_f32_e32 v11, v13, v14
	v_add_f32_e32 v14, 1.0, v16
	v_mul_f32_e32 v16, v93, v8
	v_mul_f32_e32 v17, 0xbfb8aa3b, v16
	v_rcp_f32_e32 v14, v14
	v_exp_f32_e32 v17, v17
	v_cndmask_b32_e64 v11, v13, v11, s[36:37]
	v_mov_b32_e32 v153, v3
	v_mul_f32_e32 v13, v15, v14
	v_add_f32_e32 v14, 1.0, v17
	v_mul_f32_e32 v17, v94, v8
	v_cndmask_b32_e64 v13, v15, v13, s[36:37]
	v_rcp_f32_e32 v14, v14
	v_mul_f32_e32 v15, 0xbfb8aa3b, v17
	v_exp_f32_e32 v15, v15
	v_mul_f32_e32 v14, v16, v14
	v_cndmask_b32_e64 v16, v16, v14, s[36:37]
	v_cvt_pk_bf16_f32 v14, v9, v11
	v_add_f32_e32 v9, 1.0, v15
	v_mul_f32_e32 v11, v95, v8
	v_rcp_f32_e32 v9, v9
	v_mul_f32_e32 v15, 0xbfb8aa3b, v11
	v_exp_f32_e32 v146, v15
	v_cvt_pk_bf16_f32 v15, v13, v16
	v_mul_f32_e32 v9, v17, v9
	v_mul_f32_e32 v16, v96, v8
	v_cndmask_b32_e64 v9, v17, v9, s[36:37]
	v_add_f32_e32 v13, 1.0, v146
	v_mul_f32_e32 v17, 0xbfb8aa3b, v16
	v_mul_f32_e32 v146, v97, v8
	v_exp_f32_e32 v17, v17
	v_mul_f32_e32 v148, 0xbfb8aa3b, v146
	v_exp_f32_e32 v148, v148
	v_rcp_f32_e32 v13, v13
	v_add_f32_e32 v17, 1.0, v17
	v_rcp_f32_e32 v17, v17
	v_add_f32_e32 v148, 1.0, v148
	v_rcp_f32_e32 v148, v148
; __device__ __forceinline__ unsigned pk2(float lo, float hi) { f32x2_t v = {lo, hi}; bf16x2_t b = __builtin_convertvector(v, bf16x2_t); return __builtin_bit_cast(unsigned, b); }
; __device__ __forceinline__ float fsigmoid(float x) { return __builtin_amdgcn_rcpf(1.f + fexp(-x)); }
;     ...
;         for (int tt = 0; tt < 4; ++tt) {
;           u16* srow = stg + (tt * 32 + l31) * LD;
; #pragma unroll
;           for (int ct = 0; ct < 2; ++ct)
; #pragma unroll
;             for (int rq = 0; rq < 4; ++rq) {
;               float v[4];
; #pragma unroll
;               for (int e = 0; e < 4; ++e) { v[e] = acc[ct][tt][rq * 4 + e] * rsv[tt]; if (act) v[e] = v[e] * fsigmoid(v[e]); }
;               u32x2 w; w.x = pk2(v[0], v[1]); w.y = pk2(v[2], v[3]);
;               *(u32x2*)(srow + ct * 32 + 8 * rq + 4 * h) = w;
	v_mul_f32_e32 v13, v11, v13
	v_cndmask_b32_e64 v11, v11, v13, s[36:37]
	v_mul_f32_e32 v13, v16, v17
	v_cndmask_b32_e64 v13, v16, v13, s[36:37]
	v_mul_f32_e32 v16, v146, v148
	v_cndmask_b32_e64 v17, v146, v16, s[36:37]
	v_cvt_pk_bf16_f32 v16, v9, v11
	v_mul_f32_e32 v9, v98, v8
	v_cvt_pk_bf16_f32 v17, v13, v17
	v_mul_f32_e32 v11, 0xbfb8aa3b, v9
	v_mul_f32_e32 v13, v99, v8
	v_exp_f32_e32 v11, v11
	v_mul_f32_e32 v146, 0xbfb8aa3b, v13
	v_exp_f32_e32 v146, v146
	ds_write2_b64 v7, v[14:15], v[16:17] offset0:68 offset1:70
	v_add_f32_e32 v11, 1.0, v11
	v_mul_f32_e32 v15, v100, v8
	v_rcp_f32_e32 v11, v11
	v_add_f32_e32 v14, 1.0, v146
	v_mul_f32_e32 v16, 0xbfb8aa3b, v15
	v_rcp_f32_e32 v14, v14
	v_exp_f32_e32 v16, v16
	v_mul_f32_e32 v11, v9, v11
	v_cndmask_b32_e64 v9, v9, v11, s[36:37]
	v_mul_f32_e32 v11, v13, v14
	v_add_f32_e32 v14, 1.0, v16
	v_mul_f32_e32 v16, v101, v8
	v_mul_f32_e32 v17, 0xbfb8aa3b, v16
	v_rcp_f32_e32 v14, v14
	v_exp_f32_e32 v17, v17
	v_cndmask_b32_e64 v11, v13, v11, s[36:37]
	v_mul_f32_e32 v13, v15, v14
	v_add_f32_e32 v14, 1.0, v17
	v_mul_f32_e32 v17, v102, v8
	v_cndmask_b32_e64 v13, v15, v13, s[36:37]
	v_rcp_f32_e32 v14, v14
	v_mul_f32_e32 v15, 0xbfb8aa3b, v17
	v_exp_f32_e32 v15, v15
	v_mul_f32_e32 v14, v16, v14
	v_cndmask_b32_e64 v16, v16, v14, s[36:37]
	v_cvt_pk_bf16_f32 v14, v9, v11
	v_add_f32_e32 v9, 1.0, v15
	v_mul_f32_e32 v11, v103, v8
	v_rcp_f32_e32 v9, v9
	v_mul_f32_e32 v15, 0xbfb8aa3b, v11
	v_exp_f32_e32 v146, v15
	v_cvt_pk_bf16_f32 v15, v13, v16
	v_mul_f32_e32 v9, v17, v9
	v_mul_f32_e32 v16, v104, v8
	v_cndmask_b32_e64 v9, v17, v9, s[36:37]
	v_add_f32_e32 v13, 1.0, v146
	v_mul_f32_e32 v17, 0xbfb8aa3b, v16
	v_mul_f32_e32 v146, v105, v8
	v_exp_f32_e32 v17, v17
	v_mul_f32_e32 v148, 0xbfb8aa3b, v146
	v_exp_f32_e32 v148, v148
	v_rcp_f32_e32 v13, v13
	v_add_f32_e32 v17, 1.0, v17
	v_rcp_f32_e32 v17, v17
	v_add_f32_e32 v148, 1.0, v148
	v_rcp_f32_e32 v148, v148
	v_mul_f32_e32 v13, v11, v13
	v_cndmask_b32_e64 v11, v11, v13, s[36:37]
	v_mul_f32_e32 v13, v16, v17
	v_cndmask_b32_e64 v13, v16, v13, s[36:37]
	v_mul_f32_e32 v16, v146, v148
	v_cndmask_b32_e64 v17, v146, v16, s[36:37]
	v_cvt_pk_bf16_f32 v16, v9, v11
	v_mul_f32_e32 v9, v106, v8
	v_cvt_pk_bf16_f32 v17, v13, v17
	v_mul_f32_e32 v11, 0xbfb8aa3b, v9
	v_mul_f32_e32 v13, v107, v8
	v_exp_f32_e32 v11, v11
	v_mul_f32_e32 v146, 0xbfb8aa3b, v13
	v_exp_f32_e32 v146, v146
	ds_write2_b64 v7, v[14:15], v[16:17] offset0:72 offset1:74
	v_add_f32_e32 v11, 1.0, v11
	v_mul_f32_e32 v15, v108, v8
	v_rcp_f32_e32 v11, v11
	v_add_f32_e32 v14, 1.0, v146
	v_mul_f32_e32 v16, 0xbfb8aa3b, v15
	v_rcp_f32_e32 v14, v14
	v_exp_f32_e32 v16, v16
	v_mul_f32_e32 v11, v9, v11
	v_cndmask_b32_e64 v9, v9, v11, s[36:37]
	v_mul_f32_e32 v11, v13, v14
	v_add_f32_e32 v14, 1.0, v16
	v_mul_f32_e32 v16, v109, v8
	v_mul_f32_e32 v17, 0xbfb8aa3b, v16
	v_rcp_f32_e32 v14, v14
	v_exp_f32_e32 v17, v17
	v_cndmask_b32_e64 v11, v13, v11, s[36:37]
	v_mul_f32_e32 v13, v15, v14
	v_add_f32_e32 v14, 1.0, v17
	v_mul_f32_e32 v17, v110, v8
	v_cndmask_b32_e64 v13, v15, v13, s[36:37]
	v_rcp_f32_e32 v14, v14
	v_mul_f32_e32 v15, 0xbfb8aa3b, v17
	v_exp_f32_e32 v15, v15
	v_mul_f32_e32 v14, v16, v14
	v_cndmask_b32_e64 v16, v16, v14, s[36:37]
	v_cvt_pk_bf16_f32 v14, v9, v11
	v_add_f32_e32 v9, 1.0, v15
	v_mul_f32_e32 v11, v111, v8
	v_rcp_f32_e32 v9, v9
	v_mul_f32_e32 v15, 0xbfb8aa3b, v11
	v_exp_f32_e32 v146, v15
	v_cvt_pk_bf16_f32 v15, v13, v16
	v_mul_f32_e32 v9, v17, v9
	v_mul_f32_e32 v16, v112, v8
	v_cndmask_b32_e64 v9, v17, v9, s[36:37]
	v_add_f32_e32 v13, 1.0, v146
	v_mul_f32_e32 v17, 0xbfb8aa3b, v16
	v_mul_f32_e32 v146, v113, v8
	v_exp_f32_e32 v17, v17
	v_mul_f32_e32 v148, 0xbfb8aa3b, v146
	v_exp_f32_e32 v148, v148
	v_rcp_f32_e32 v13, v13
	v_add_f32_e32 v17, 1.0, v17
	v_rcp_f32_e32 v17, v17
	v_add_f32_e32 v148, 1.0, v148
	v_rcp_f32_e32 v148, v148
	v_mul_f32_e32 v13, v11, v13
	v_cndmask_b32_e64 v11, v11, v13, s[36:37]
	v_mul_f32_e32 v13, v16, v17
	v_cndmask_b32_e64 v13, v16, v13, s[36:37]
	v_mul_f32_e32 v16, v146, v148
	v_cndmask_b32_e64 v17, v146, v16, s[36:37]
	v_cvt_pk_bf16_f32 v16, v9, v11
	s_waitcnt vmcnt(1)
	v_mul_f32_e32 v9, v50, v6
	v_cvt_pk_bf16_f32 v17, v13, v17
	v_mul_f32_e32 v11, 0xbfb8aa3b, v9
	v_mul_f32_e32 v13, v51, v6
	v_exp_f32_e32 v11, v11
	v_mul_f32_e32 v146, 0xbfb8aa3b, v13
	v_exp_f32_e32 v146, v146
	ds_write2_b64 v7, v[14:15], v[16:17] offset0:76 offset1:78
	v_add_f32_e32 v7, 1.0, v11
	v_mul_f32_e32 v14, v52, v6
	v_rcp_f32_e32 v7, v7
	v_add_f32_e32 v11, 1.0, v146
	v_mul_f32_e32 v15, 0xbfb8aa3b, v14
	v_rcp_f32_e32 v11, v11
	v_exp_f32_e32 v15, v15
	v_mul_f32_e32 v7, v9, v7
	v_cndmask_b32_e64 v7, v9, v7, s[36:37]
	v_mul_f32_e32 v9, v13, v11
	v_add_f32_e32 v11, 1.0, v15
	v_mul_f32_e32 v15, v53, v6
	v_mul_f32_e32 v16, 0xbfb8aa3b, v15
	v_rcp_f32_e32 v11, v11
	v_exp_f32_e32 v16, v16
	v_cndmask_b32_e64 v9, v13, v9, s[36:37]
	v_mul_f32_e32 v11, v14, v11
	v_add_f32_e32 v13, 1.0, v16
	v_mul_f32_e32 v16, v54, v6
	v_cndmask_b32_e64 v11, v14, v11, s[36:37]
	v_mul_f32_e32 v14, 0xbfb8aa3b, v16
	v_rcp_f32_e32 v13, v13
	v_exp_f32_e32 v17, v14
	v_cvt_pk_bf16_f32 v14, v7, v9
	v_mul_f32_e32 v9, v55, v6
	v_mul_f32_e32 v13, v15, v13
	v_add_f32_e32 v7, 1.0, v17
	v_cndmask_b32_e64 v13, v15, v13, s[36:37]
	v_rcp_f32_e32 v7, v7
	v_mul_f32_e32 v15, 0xbfb8aa3b, v9
	v_exp_f32_e32 v17, v15
	v_cvt_pk_bf16_f32 v15, v11, v13
	v_mul_f32_e32 v7, v16, v7
	v_mul_f32_e32 v13, v56, v6
	v_cndmask_b32_e64 v7, v16, v7, s[36:37]
	v_add_f32_e32 v11, 1.0, v17
	v_mul_f32_e32 v16, 0xbfb8aa3b, v13
	v_mul_f32_e32 v17, v57, v6
	v_exp_f32_e32 v16, v16
	v_mul_f32_e32 v146, 0xbfb8aa3b, v17
	v_exp_f32_e32 v146, v146
	v_rcp_f32_e32 v11, v11
	v_add_f32_e32 v16, 1.0, v16
; __device__ __forceinline__ unsigned pk2(float lo, float hi) { f32x2_t v = {lo, hi}; bf16x2_t b = __builtin_convertvector(v, bf16x2_t); return __builtin_bit_cast(unsigned, b); }
; __device__ __forceinline__ float fsigmoid(float x) { return __builtin_amdgcn_rcpf(1.f + fexp(-x)); }
;     ...
;         for (int tt = 0; tt < 4; ++tt) {
;           u16* srow = stg + (tt * 32 + l31) * LD;
; #pragma unroll
;           for (int ct = 0; ct < 2; ++ct)
; #pragma unroll
;             for (int rq = 0; rq < 4; ++rq) {
;               float v[4];
; #pragma unroll
;               for (int e = 0; e < 4; ++e) { v[e] = acc[ct][tt][rq * 4 + e] * rsv[tt]; if (act) v[e] = v[e] * fsigmoid(v[e]); }
;               u32x2 w; w.x = pk2(v[0], v[1]); w.y = pk2(v[2], v[3]);
;               *(u32x2*)(srow + ct * 32 + 8 * rq + 4 * h) = w;
	v_rcp_f32_e32 v16, v16
	v_add_f32_e32 v146, 1.0, v146
	v_rcp_f32_e32 v146, v146
	v_mul_f32_e32 v11, v9, v11
	v_cndmask_b32_e64 v9, v9, v11, s[36:37]
	v_mul_f32_e32 v11, v13, v16
	v_cndmask_b32_e64 v11, v13, v11, s[36:37]
	v_mul_f32_e32 v13, v17, v146
	v_cndmask_b32_e64 v13, v17, v13, s[36:37]
	v_cvt_pk_bf16_f32 v16, v7, v9
	v_mul_f32_e32 v9, v58, v6
	v_cvt_pk_bf16_f32 v17, v11, v13
	v_mul_f32_e32 v11, 0xbfb8aa3b, v9
	v_mul_f32_e32 v13, v59, v6
	v_exp_f32_e32 v11, v11
	v_mul_f32_e32 v146, 0xbfb8aa3b, v13
	v_exp_f32_e32 v146, v146
	v_add_u32_e32 v7, 0x2000, v2
	ds_write2_b64 v7, v[14:15], v[16:17] offset0:128 offset1:130
	v_add_f32_e32 v11, 1.0, v11
	v_mul_f32_e32 v15, v60, v6
	v_rcp_f32_e32 v11, v11
	v_add_f32_e32 v14, 1.0, v146
	v_mul_f32_e32 v16, 0xbfb8aa3b, v15
	v_rcp_f32_e32 v14, v14
	v_exp_f32_e32 v16, v16
	v_mul_f32_e32 v11, v9, v11
	v_cndmask_b32_e64 v9, v9, v11, s[36:37]
	v_mul_f32_e32 v11, v13, v14
	v_add_f32_e32 v14, 1.0, v16
	v_mul_f32_e32 v16, v61, v6
	v_mul_f32_e32 v17, 0xbfb8aa3b, v16
	v_rcp_f32_e32 v14, v14
	v_exp_f32_e32 v17, v17
	v_cndmask_b32_e64 v11, v13, v11, s[36:37]
	v_add_u32_e32 v2, 0x3000, v2
	v_mul_f32_e32 v13, v15, v14
	v_add_f32_e32 v14, 1.0, v17
	v_mul_f32_e32 v17, v62, v6
	v_cndmask_b32_e64 v13, v15, v13, s[36:37]
	v_rcp_f32_e32 v14, v14
	v_mul_f32_e32 v15, 0xbfb8aa3b, v17
	v_exp_f32_e32 v15, v15
	v_mul_f32_e32 v14, v16, v14
	v_cndmask_b32_e64 v16, v16, v14, s[36:37]
	v_cvt_pk_bf16_f32 v14, v9, v11
	v_add_f32_e32 v9, 1.0, v15
	v_mul_f32_e32 v11, v63, v6
	v_rcp_f32_e32 v9, v9
	v_mul_f32_e32 v15, 0xbfb8aa3b, v11
	v_exp_f32_e32 v146, v15
	v_cvt_pk_bf16_f32 v15, v13, v16
	v_mul_f32_e32 v9, v17, v9
	v_mul_f32_e32 v16, v64, v6
	v_cndmask_b32_e64 v9, v17, v9, s[36:37]
	v_add_f32_e32 v13, 1.0, v146
	v_mul_f32_e32 v17, 0xbfb8aa3b, v16
	v_mul_f32_e32 v146, v65, v6
	v_exp_f32_e32 v17, v17
	v_mul_f32_e32 v148, 0xbfb8aa3b, v146
	v_exp_f32_e32 v148, v148
	v_rcp_f32_e32 v13, v13
	v_add_f32_e32 v17, 1.0, v17
	v_rcp_f32_e32 v17, v17
	v_add_f32_e32 v148, 1.0, v148
	v_rcp_f32_e32 v148, v148
	v_mul_f32_e32 v13, v11, v13
	v_cndmask_b32_e64 v11, v11, v13, s[36:37]
	v_mul_f32_e32 v13, v16, v17
	v_cndmask_b32_e64 v13, v16, v13, s[36:37]
	v_mul_f32_e32 v16, v146, v148
	v_cndmask_b32_e64 v17, v146, v16, s[36:37]
	v_cvt_pk_bf16_f32 v16, v9, v11
	v_mul_f32_e32 v9, v66, v6
	v_cvt_pk_bf16_f32 v17, v13, v17
	v_mul_f32_e32 v11, 0xbfb8aa3b, v9
	v_mul_f32_e32 v13, v67, v6
	v_exp_f32_e32 v11, v11
	v_mul_f32_e32 v146, 0xbfb8aa3b, v13
	v_exp_f32_e32 v146, v146
	ds_write2_b64 v7, v[14:15], v[16:17] offset0:132 offset1:134
	v_add_f32_e32 v11, 1.0, v11
	v_mul_f32_e32 v15, v68, v6
	v_rcp_f32_e32 v11, v11
	v_add_f32_e32 v14, 1.0, v146
	v_mul_f32_e32 v16, 0xbfb8aa3b, v15
	v_rcp_f32_e32 v14, v14
	v_exp_f32_e32 v16, v16
	v_mul_f32_e32 v11, v9, v11
	v_cndmask_b32_e64 v9, v9, v11, s[36:37]
	v_mul_f32_e32 v11, v13, v14
	v_add_f32_e32 v14, 1.0, v16
	v_mul_f32_e32 v16, v69, v6
	v_mul_f32_e32 v17, 0xbfb8aa3b, v16
	v_rcp_f32_e32 v14, v14
	v_exp_f32_e32 v17, v17
	v_cndmask_b32_e64 v11, v13, v11, s[36:37]
	v_mul_f32_e32 v13, v15, v14
	v_add_f32_e32 v14, 1.0, v17
	v_mul_f32_e32 v17, v70, v6
	v_cndmask_b32_e64 v13, v15, v13, s[36:37]
	v_rcp_f32_e32 v14, v14
	v_mul_f32_e32 v15, 0xbfb8aa3b, v17
	v_exp_f32_e32 v15, v15
	v_mul_f32_e32 v14, v16, v14
	v_cndmask_b32_e64 v16, v16, v14, s[36:37]
	v_cvt_pk_bf16_f32 v14, v9, v11
	v_add_f32_e32 v9, 1.0, v15
	v_mul_f32_e32 v11, v71, v6
	v_rcp_f32_e32 v9, v9
	v_mul_f32_e32 v15, 0xbfb8aa3b, v11
	v_exp_f32_e32 v146, v15
	v_cvt_pk_bf16_f32 v15, v13, v16
	v_mul_f32_e32 v9, v17, v9
	v_mul_f32_e32 v16, v72, v6
	v_cndmask_b32_e64 v9, v17, v9, s[36:37]
	v_add_f32_e32 v13, 1.0, v146
	v_mul_f32_e32 v17, 0xbfb8aa3b, v16
	v_mul_f32_e32 v146, v73, v6
	v_exp_f32_e32 v17, v17
	v_mul_f32_e32 v148, 0xbfb8aa3b, v146
	v_exp_f32_e32 v148, v148
	v_rcp_f32_e32 v13, v13
	v_add_f32_e32 v17, 1.0, v17
	v_rcp_f32_e32 v17, v17
	v_add_f32_e32 v148, 1.0, v148
	v_rcp_f32_e32 v148, v148
	v_mul_f32_e32 v13, v11, v13
	v_cndmask_b32_e64 v11, v11, v13, s[36:37]
	v_mul_f32_e32 v13, v16, v17
	v_cndmask_b32_e64 v13, v16, v13, s[36:37]
	v_mul_f32_e32 v16, v146, v148
	v_cndmask_b32_e64 v17, v146, v16, s[36:37]
	v_cvt_pk_bf16_f32 v16, v9, v11
	v_mul_f32_e32 v9, v74, v6
	v_cvt_pk_bf16_f32 v17, v13, v17
	v_mul_f32_e32 v11, 0xbfb8aa3b, v9
	v_mul_f32_e32 v13, v75, v6
	v_exp_f32_e32 v11, v11
	v_mul_f32_e32 v146, 0xbfb8aa3b, v13
	v_exp_f32_e32 v146, v146
	ds_write2_b64 v7, v[14:15], v[16:17] offset0:136 offset1:138
	v_add_f32_e32 v11, 1.0, v11
	v_mul_f32_e32 v15, v76, v6
	v_rcp_f32_e32 v11, v11
	v_add_f32_e32 v14, 1.0, v146
	v_mul_f32_e32 v16, 0xbfb8aa3b, v15
	v_rcp_f32_e32 v14, v14
	v_exp_f32_e32 v16, v16
	v_mul_f32_e32 v11, v9, v11
	v_cndmask_b32_e64 v9, v9, v11, s[36:37]
	v_mul_f32_e32 v11, v13, v14
	v_add_f32_e32 v14, 1.0, v16
	v_mul_f32_e32 v16, v77, v6
	v_mul_f32_e32 v17, 0xbfb8aa3b, v16
	v_rcp_f32_e32 v14, v14
	v_exp_f32_e32 v17, v17
	v_cndmask_b32_e64 v11, v13, v11, s[36:37]
	v_mul_f32_e32 v13, v15, v14
	v_add_f32_e32 v14, 1.0, v17
	v_mul_f32_e32 v17, v78, v6
	v_cndmask_b32_e64 v13, v15, v13, s[36:37]
	v_rcp_f32_e32 v14, v14
	v_mul_f32_e32 v15, 0xbfb8aa3b, v17
	v_exp_f32_e32 v15, v15
	v_mul_f32_e32 v14, v16, v14
	v_cndmask_b32_e64 v16, v16, v14, s[36:37]
	v_cvt_pk_bf16_f32 v14, v9, v11
	v_add_f32_e32 v9, 1.0, v15
	v_mul_f32_e32 v11, v79, v6
	v_rcp_f32_e32 v9, v9
	v_mul_f32_e32 v15, 0xbfb8aa3b, v11
	v_exp_f32_e32 v146, v15
	v_cvt_pk_bf16_f32 v15, v13, v16
	v_mul_f32_e32 v9, v17, v9
	v_mul_f32_e32 v16, v80, v6
	v_cndmask_b32_e64 v9, v17, v9, s[36:37]
	v_add_f32_e32 v13, 1.0, v146
	v_mul_f32_e32 v17, 0xbfb8aa3b, v16
	v_mul_f32_e32 v146, v81, v6
	v_exp_f32_e32 v17, v17
	v_mul_f32_e32 v148, 0xbfb8aa3b, v146
	v_exp_f32_e32 v148, v148
	v_rcp_f32_e32 v13, v13
	v_add_f32_e32 v17, 1.0, v17
	v_rcp_f32_e32 v17, v17
	v_add_f32_e32 v148, 1.0, v148
	v_rcp_f32_e32 v148, v148
	v_mul_f32_e32 v13, v11, v13
	v_cndmask_b32_e64 v11, v11, v13, s[36:37]
	v_mul_f32_e32 v13, v16, v17
	v_cndmask_b32_e64 v13, v16, v13, s[36:37]
	v_mul_f32_e32 v16, v146, v148
	v_cndmask_b32_e64 v17, v146, v16, s[36:37]
	v_cvt_pk_bf16_f32 v16, v9, v11
	s_waitcnt vmcnt(0)
; __device__ __forceinline__ unsigned pk2(float lo, float hi) { f32x2_t v = {lo, hi}; bf16x2_t b = __builtin_convertvector(v, bf16x2_t); return __builtin_bit_cast(unsigned, b); }
; __device__ __forceinline__ float fsigmoid(float x) { return __builtin_amdgcn_rcpf(1.f + fexp(-x)); }
;     ...
;         for (int tt = 0; tt < 4; ++tt) {
;           u16* srow = stg + (tt * 32 + l31) * LD;
; #pragma unroll
;           for (int ct = 0; ct < 2; ++ct)
; #pragma unroll
;             for (int rq = 0; rq < 4; ++rq) {
;               float v[4];
; #pragma unroll
;               for (int e = 0; e < 4; ++e) { v[e] = acc[ct][tt][rq * 4 + e] * rsv[tt]; if (act) v[e] = v[e] * fsigmoid(v[e]); }
;               u32x2 w; w.x = pk2(v[0], v[1]); w.y = pk2(v[2], v[3]);
;               *(u32x2*)(srow + ct * 32 + 8 * rq + 4 * h) = w;
	v_mul_f32_e32 v9, v18, v4
	v_cvt_pk_bf16_f32 v17, v13, v17
	v_mul_f32_e32 v11, 0xbfb8aa3b, v9
	v_mul_f32_e32 v13, v19, v4
	v_exp_f32_e32 v11, v11
	v_mul_f32_e32 v146, 0xbfb8aa3b, v13
	v_exp_f32_e32 v146, v146
	ds_write2_b64 v7, v[14:15], v[16:17] offset0:140 offset1:142
	v_add_f32_e32 v7, 1.0, v11
	v_mul_f32_e32 v14, v20, v4
	v_rcp_f32_e32 v7, v7
	v_add_f32_e32 v11, 1.0, v146
	v_mul_f32_e32 v15, 0xbfb8aa3b, v14
	v_rcp_f32_e32 v11, v11
	v_exp_f32_e32 v15, v15
	v_mul_f32_e32 v7, v9, v7
	v_cndmask_b32_e64 v7, v9, v7, s[36:37]
	v_mul_f32_e32 v9, v13, v11
	v_add_f32_e32 v11, 1.0, v15
	v_mul_f32_e32 v15, v21, v4
	v_mul_f32_e32 v16, 0xbfb8aa3b, v15
	v_rcp_f32_e32 v11, v11
	v_exp_f32_e32 v16, v16
	v_cndmask_b32_e64 v9, v13, v9, s[36:37]
	v_mul_f32_e32 v11, v14, v11
	v_add_f32_e32 v13, 1.0, v16
	v_mul_f32_e32 v16, v22, v4
	v_cndmask_b32_e64 v11, v14, v11, s[36:37]
	v_mul_f32_e32 v14, 0xbfb8aa3b, v16
	v_rcp_f32_e32 v13, v13
	v_exp_f32_e32 v17, v14
	v_cvt_pk_bf16_f32 v14, v7, v9
	v_mul_f32_e32 v9, v23, v4
	v_mul_f32_e32 v13, v15, v13
	v_add_f32_e32 v7, 1.0, v17
	v_cndmask_b32_e64 v13, v15, v13, s[36:37]
	v_rcp_f32_e32 v7, v7
	v_mul_f32_e32 v15, 0xbfb8aa3b, v9
	v_exp_f32_e32 v17, v15
	v_cvt_pk_bf16_f32 v15, v11, v13
	v_mul_f32_e32 v7, v16, v7
	v_mul_f32_e32 v13, v24, v4
	v_cndmask_b32_e64 v7, v16, v7, s[36:37]
	v_add_f32_e32 v11, 1.0, v17
	v_mul_f32_e32 v16, 0xbfb8aa3b, v13
	v_mul_f32_e32 v17, v25, v4
	v_exp_f32_e32 v16, v16
	v_mul_f32_e32 v146, 0xbfb8aa3b, v17
	v_exp_f32_e32 v146, v146
	v_rcp_f32_e32 v11, v11
	v_add_f32_e32 v16, 1.0, v16
	v_rcp_f32_e32 v16, v16
	v_add_f32_e32 v146, 1.0, v146
	v_rcp_f32_e32 v146, v146
	v_mul_f32_e32 v11, v9, v11
	v_cndmask_b32_e64 v9, v9, v11, s[36:37]
	v_mul_f32_e32 v11, v13, v16
	v_cndmask_b32_e64 v11, v13, v11, s[36:37]
	v_mul_f32_e32 v13, v17, v146
	v_cndmask_b32_e64 v13, v17, v13, s[36:37]
	v_cvt_pk_bf16_f32 v16, v7, v9
	v_mul_f32_e32 v7, v26, v4
	v_cvt_pk_bf16_f32 v17, v11, v13
	v_mul_f32_e32 v9, 0xbfb8aa3b, v7
	v_mul_f32_e32 v11, v27, v4
	v_exp_f32_e32 v9, v9
	v_mul_f32_e32 v13, 0xbfb8aa3b, v11
	v_exp_f32_e32 v13, v13
	ds_write2_b64 v2, v[14:15], v[16:17] offset0:192 offset1:194
	v_add_f32_e32 v9, 1.0, v9
	v_mul_f32_e32 v14, v28, v4
	v_rcp_f32_e32 v9, v9
	v_add_f32_e32 v13, 1.0, v13
	v_mul_f32_e32 v15, 0xbfb8aa3b, v14
	v_rcp_f32_e32 v13, v13
	v_exp_f32_e32 v15, v15
	v_mul_f32_e32 v9, v7, v9
	v_cndmask_b32_e64 v7, v7, v9, s[36:37]
	v_mul_f32_e32 v9, v11, v13
	v_add_f32_e32 v13, 1.0, v15
	v_mul_f32_e32 v15, v29, v4
	v_mul_f32_e32 v16, 0xbfb8aa3b, v15
	v_rcp_f32_e32 v13, v13
	v_exp_f32_e32 v16, v16
	v_cndmask_b32_e64 v9, v11, v9, s[36:37]
	v_mul_f32_e32 v11, v14, v13
	v_add_f32_e32 v13, 1.0, v16
	v_mul_f32_e32 v16, v30, v4
	v_cndmask_b32_e64 v11, v14, v11, s[36:37]
	v_mul_f32_e32 v14, 0xbfb8aa3b, v16
	v_rcp_f32_e32 v13, v13
	v_exp_f32_e32 v17, v14
	v_cvt_pk_bf16_f32 v14, v7, v9
	v_mul_f32_e32 v9, v31, v4
	v_mul_f32_e32 v13, v15, v13
	v_add_f32_e32 v7, 1.0, v17
	v_cndmask_b32_e64 v13, v15, v13, s[36:37]
	v_rcp_f32_e32 v7, v7
	v_mul_f32_e32 v15, 0xbfb8aa3b, v9
	v_exp_f32_e32 v17, v15
	v_cvt_pk_bf16_f32 v15, v11, v13
	v_mul_f32_e32 v7, v16, v7
	v_mul_f32_e32 v13, v32, v4
	v_cndmask_b32_e64 v7, v16, v7, s[36:37]
	v_add_f32_e32 v11, 1.0, v17
	v_mul_f32_e32 v16, 0xbfb8aa3b, v13
	v_mul_f32_e32 v17, v33, v4
	v_exp_f32_e32 v16, v16
	v_mul_f32_e32 v146, 0xbfb8aa3b, v17
	v_exp_f32_e32 v146, v146
	v_rcp_f32_e32 v11, v11
	v_add_f32_e32 v16, 1.0, v16
	v_rcp_f32_e32 v16, v16
	v_add_f32_e32 v146, 1.0, v146
	v_rcp_f32_e32 v146, v146
	v_mul_f32_e32 v11, v9, v11
	v_cndmask_b32_e64 v9, v9, v11, s[36:37]
	v_mul_f32_e32 v11, v13, v16
	v_cndmask_b32_e64 v11, v13, v11, s[36:37]
	v_mul_f32_e32 v13, v17, v146
	v_cndmask_b32_e64 v13, v17, v13, s[36:37]
	v_cvt_pk_bf16_f32 v16, v7, v9
	v_mul_f32_e32 v7, v34, v4
	v_cvt_pk_bf16_f32 v17, v11, v13
	v_mul_f32_e32 v9, 0xbfb8aa3b, v7
	v_mul_f32_e32 v11, v35, v4
	v_exp_f32_e32 v9, v9
	v_mul_f32_e32 v13, 0xbfb8aa3b, v11
	v_exp_f32_e32 v13, v13
	ds_write2_b64 v2, v[14:15], v[16:17] offset0:196 offset1:198
	v_add_f32_e32 v9, 1.0, v9
	v_mul_f32_e32 v14, v36, v4
	v_rcp_f32_e32 v9, v9
	v_add_f32_e32 v13, 1.0, v13
	v_mul_f32_e32 v15, 0xbfb8aa3b, v14
	v_rcp_f32_e32 v13, v13
	v_exp_f32_e32 v15, v15
	v_mul_f32_e32 v9, v7, v9
	v_cndmask_b32_e64 v7, v7, v9, s[36:37]
	v_mul_f32_e32 v9, v11, v13
	v_add_f32_e32 v13, 1.0, v15
	v_mul_f32_e32 v15, v37, v4
	v_mul_f32_e32 v16, 0xbfb8aa3b, v15
	v_rcp_f32_e32 v13, v13
	v_exp_f32_e32 v16, v16
	v_cndmask_b32_e64 v9, v11, v9, s[36:37]
	v_mul_f32_e32 v11, v14, v13
	v_add_f32_e32 v13, 1.0, v16
	v_mul_f32_e32 v16, v38, v4
	v_cndmask_b32_e64 v11, v14, v11, s[36:37]
	v_mul_f32_e32 v14, 0xbfb8aa3b, v16
	v_rcp_f32_e32 v13, v13
	v_exp_f32_e32 v17, v14
	v_cvt_pk_bf16_f32 v14, v7, v9
	v_mul_f32_e32 v9, v39, v4
	v_mul_f32_e32 v13, v15, v13
	v_add_f32_e32 v7, 1.0, v17
	v_cndmask_b32_e64 v13, v15, v13, s[36:37]
	v_rcp_f32_e32 v7, v7
	v_mul_f32_e32 v15, 0xbfb8aa3b, v9
	v_exp_f32_e32 v17, v15
	v_cvt_pk_bf16_f32 v15, v11, v13
	v_mul_f32_e32 v7, v16, v7
	v_mul_f32_e32 v13, v40, v4
	v_cndmask_b32_e64 v7, v16, v7, s[36:37]
	v_add_f32_e32 v11, 1.0, v17
	v_mul_f32_e32 v16, 0xbfb8aa3b, v13
	v_mul_f32_e32 v17, v41, v4
	v_exp_f32_e32 v16, v16
	v_mul_f32_e32 v146, 0xbfb8aa3b, v17
	v_exp_f32_e32 v146, v146
	v_rcp_f32_e32 v11, v11
	v_add_f32_e32 v16, 1.0, v16
	v_rcp_f32_e32 v16, v16
	v_add_f32_e32 v146, 1.0, v146
	v_rcp_f32_e32 v146, v146
	v_mul_f32_e32 v11, v9, v11
	v_cndmask_b32_e64 v9, v9, v11, s[36:37]
	v_mul_f32_e32 v11, v13, v16
	v_cndmask_b32_e64 v11, v13, v11, s[36:37]
	v_mul_f32_e32 v13, v17, v146
	v_cndmask_b32_e64 v13, v17, v13, s[36:37]
	v_cvt_pk_bf16_f32 v16, v7, v9
	v_mul_f32_e32 v7, v42, v4
; __device__ __forceinline__ unsigned pk2(float lo, float hi) { f32x2_t v = {lo, hi}; bf16x2_t b = __builtin_convertvector(v, bf16x2_t); return __builtin_bit_cast(unsigned, b); }
; __device__ __forceinline__ float fsigmoid(float x) { return __builtin_amdgcn_rcpf(1.f + fexp(-x)); }
;     ...
;       auto flush_rows = [&](u16* gbase, size_t ldd) {
; #pragma unroll
;         for (int it = 0; it < 16; ++it) {
;           const int r = it * 8 + (lane >> 3), ch = lane & 7;
;           *(u32x4*)(gbase + (size_t)r * ldd + ch * 8) = *(const u32x4*)(stg + r * LD + ch * 8);
;         }
;       };
;     ...
;         for (int tt = 0; tt < 4; ++tt) {
;           u16* srow = stg + (tt * 32 + l31) * LD;
; #pragma unroll
;           for (int ct = 0; ct < 2; ++ct)
; #pragma unroll
;             for (int rq = 0; rq < 4; ++rq) {
;               float v[4];
; #pragma unroll
;               for (int e = 0; e < 4; ++e) { v[e] = acc[ct][tt][rq * 4 + e] * rsv[tt]; if (act) v[e] = v[e] * fsigmoid(v[e]); }
;               u32x2 w; w.x = pk2(v[0], v[1]); w.y = pk2(v[2], v[3]);
;               *(u32x2*)(srow + ct * 32 + 8 * rq + 4 * h) = w;
	v_cvt_pk_bf16_f32 v17, v11, v13
	v_mul_f32_e32 v9, 0xbfb8aa3b, v7
	v_mul_f32_e32 v11, v43, v4
	v_exp_f32_e32 v9, v9
	v_mul_f32_e32 v13, 0xbfb8aa3b, v11
	v_exp_f32_e32 v13, v13
	ds_write2_b64 v2, v[14:15], v[16:17] offset0:200 offset1:202
	v_add_f32_e32 v9, 1.0, v9
	v_mul_f32_e32 v14, v44, v4
	v_rcp_f32_e32 v9, v9
	v_add_f32_e32 v13, 1.0, v13
	v_mul_f32_e32 v15, 0xbfb8aa3b, v14
	v_rcp_f32_e32 v13, v13
	v_exp_f32_e32 v15, v15
	v_mul_f32_e32 v9, v7, v9
	v_cndmask_b32_e64 v7, v7, v9, s[36:37]
	v_mul_f32_e32 v9, v11, v13
	v_add_f32_e32 v13, 1.0, v15
	v_mul_f32_e32 v15, v45, v4
	v_mul_f32_e32 v16, 0xbfb8aa3b, v15
	v_rcp_f32_e32 v13, v13
	v_exp_f32_e32 v16, v16
	v_cndmask_b32_e64 v9, v11, v9, s[36:37]
	v_mul_f32_e32 v11, v14, v13
	v_add_f32_e32 v13, 1.0, v16
	v_mul_f32_e32 v16, v46, v4
	v_cndmask_b32_e64 v11, v14, v11, s[36:37]
	v_mul_f32_e32 v14, 0xbfb8aa3b, v16
	v_rcp_f32_e32 v13, v13
	v_exp_f32_e32 v17, v14
	v_cvt_pk_bf16_f32 v14, v7, v9
	v_mul_f32_e32 v9, v47, v4
	v_mul_f32_e32 v13, v15, v13
	v_add_f32_e32 v7, 1.0, v17
	v_cndmask_b32_e64 v13, v15, v13, s[36:37]
	v_rcp_f32_e32 v7, v7
	v_mul_f32_e32 v15, 0xbfb8aa3b, v9
	v_exp_f32_e32 v17, v15
	v_cvt_pk_bf16_f32 v15, v11, v13
	v_mul_f32_e32 v7, v16, v7
	v_mul_f32_e32 v13, v48, v4
	v_cndmask_b32_e64 v7, v16, v7, s[36:37]
	v_add_f32_e32 v11, 1.0, v17
	v_mul_f32_e32 v16, 0xbfb8aa3b, v13
	v_mul_f32_e32 v17, v49, v4
	v_exp_f32_e32 v16, v16
	v_mul_f32_e32 v146, 0xbfb8aa3b, v17
	v_exp_f32_e32 v146, v146
	v_rcp_f32_e32 v11, v11
	v_add_f32_e32 v16, 1.0, v16
	v_rcp_f32_e32 v16, v16
	v_add_f32_e32 v146, 1.0, v146
	v_rcp_f32_e32 v146, v146
	v_mul_f32_e32 v11, v9, v11
	v_cndmask_b32_e64 v9, v9, v11, s[36:37]
	v_mul_f32_e32 v11, v13, v16
	v_cndmask_b32_e64 v11, v13, v11, s[36:37]
	v_mul_f32_e32 v13, v17, v146
	v_cndmask_b32_e64 v13, v17, v13, s[36:37]
	s_mul_hi_i32 s37, s34, s31
	s_mul_i32 s36, s34, s31
	s_lshl_b64 s[36:37], s[36:37], 1
	v_cvt_pk_bf16_f32 v16, v7, v9
	v_cvt_pk_bf16_f32 v17, v11, v13
	s_waitcnt lgkmcnt(0)
	s_add_u32 s31, s38, s36
	v_lshrrev_b32_e32 v7, 3, v147
	v_lshlrev_b32_e32 v9, 4, v225
	ds_write2_b64 v2, v[14:15], v[16:17] offset0:204 offset1:206
	s_addc_u32 s35, s39, s37
	s_lshl_b64 s[36:37], s[20:21], 1
	v_mul_u32_u24_e32 v2, 0x90, v7
	v_and_b32_e32 v152, 0x70, v9
	s_add_u32 s36, s31, s36
	v_add3_u32 v9, s7, v2, v152
	v_mul_u32_u24_e32 v2, s34, v7
	s_addc_u32 s37, s35, s37
	ds_read_b128 v[14:17], v9
	v_lshlrev_b32_e32 v2, 1, v2
	v_lshl_add_u64 v[148:149], s[36:37], 0, v[2:3]
	v_lshl_add_u64 v[154:155], v[148:149], 0, v[152:153]
	ds_read_b128 v[148:151], v9 offset:1152
	v_or_b32_e32 v2, 8, v7
	v_mul_u32_u24_e32 v2, s34, v2
	v_lshlrev_b32_e32 v2, 1, v2
	s_waitcnt lgkmcnt(1)
	global_store_dwordx4 v[154:155], v[14:17], off
	s_nop 1
	v_lshl_add_u64 v[14:15], s[36:37], 0, v[2:3]
	v_or_b32_e32 v2, 16, v7
	v_lshl_add_u64 v[14:15], v[14:15], 0, v[152:153]
	v_mul_u32_u24_e32 v2, s34, v2
	s_waitcnt lgkmcnt(0)
	global_store_dwordx4 v[14:15], v[148:151], off
	ds_read_b128 v[14:17], v9 offset:2304
	v_lshlrev_b32_e32 v2, 1, v2
	v_lshl_add_u64 v[148:149], s[36:37], 0, v[2:3]
	v_lshl_add_u64 v[154:155], v[148:149], 0, v[152:153]
	ds_read_b128 v[148:151], v9 offset:3456
	v_or_b32_e32 v2, 24, v7
	v_mul_u32_u24_e32 v2, s34, v2
	v_lshlrev_b32_e32 v2, 1, v2
	s_waitcnt lgkmcnt(1)
	global_store_dwordx4 v[154:155], v[14:17], off
	s_nop 1
	v_lshl_add_u64 v[14:15], s[36:37], 0, v[2:3]
	v_or_b32_e32 v2, 32, v7
	v_lshl_add_u64 v[14:15], v[14:15], 0, v[152:153]
	v_mul_u32_u24_e32 v2, s34, v2
	s_waitcnt lgkmcnt(0)
;     ...
;       auto flush_rows = [&](u16* gbase, size_t ldd) {
; #pragma unroll
;         for (int it = 0; it < 16; ++it) {
;           const int r = it * 8 + (lane >> 3), ch = lane & 7;
;           *(u32x4*)(gbase + (size_t)r * ldd + ch * 8) = *(const u32x4*)(stg + r * LD + ch * 8);
;         }
;       };
;     ...
;         flush_rows(dst + (size_t)(m0 + wr * 128) * ldd + c0, (size_t)ldd);
	global_store_dwordx4 v[14:15], v[148:151], off
	ds_read_b128 v[14:17], v9 offset:4608
	v_lshlrev_b32_e32 v2, 1, v2
	v_lshl_add_u64 v[148:149], s[36:37], 0, v[2:3]
	v_lshl_add_u64 v[154:155], v[148:149], 0, v[152:153]
	ds_read_b128 v[148:151], v9 offset:5760
	v_or_b32_e32 v2, 40, v7
	v_mul_u32_u24_e32 v2, s34, v2
	v_lshlrev_b32_e32 v2, 1, v2
	s_waitcnt lgkmcnt(1)
	global_store_dwordx4 v[154:155], v[14:17], off
	s_nop 1
	v_lshl_add_u64 v[14:15], s[36:37], 0, v[2:3]
	v_or_b32_e32 v2, 48, v7
	v_lshl_add_u64 v[14:15], v[14:15], 0, v[152:153]
	v_mul_u32_u24_e32 v2, s34, v2
	s_waitcnt lgkmcnt(0)
	global_store_dwordx4 v[14:15], v[148:151], off
	ds_read_b128 v[14:17], v9 offset:6912
	v_lshlrev_b32_e32 v2, 1, v2
	v_lshl_add_u64 v[148:149], s[36:37], 0, v[2:3]
	v_lshl_add_u64 v[154:155], v[148:149], 0, v[152:153]
	ds_read_b128 v[148:151], v9 offset:8064
	v_or_b32_e32 v2, 56, v7
	v_mul_u32_u24_e32 v2, s34, v2
	v_lshlrev_b32_e32 v2, 1, v2
	s_waitcnt lgkmcnt(1)
	global_store_dwordx4 v[154:155], v[14:17], off
	s_nop 1
	v_lshl_add_u64 v[14:15], s[36:37], 0, v[2:3]
	v_or_b32_e32 v2, 64, v7
	v_lshl_add_u64 v[14:15], v[14:15], 0, v[152:153]
	v_mul_u32_u24_e32 v2, s34, v2
	s_waitcnt lgkmcnt(0)
	global_store_dwordx4 v[14:15], v[148:151], off
	ds_read_b128 v[14:17], v9 offset:9216
	v_lshlrev_b32_e32 v2, 1, v2
	v_lshl_add_u64 v[148:149], s[36:37], 0, v[2:3]
	v_lshl_add_u64 v[154:155], v[148:149], 0, v[152:153]
	ds_read_b128 v[148:151], v9 offset:10368
	v_or_b32_e32 v2, 0x48, v7
	v_mul_u32_u24_e32 v2, s34, v2
	v_lshlrev_b32_e32 v2, 1, v2
	s_waitcnt lgkmcnt(1)
	global_store_dwordx4 v[154:155], v[14:17], off
	s_nop 1
	v_lshl_add_u64 v[14:15], s[36:37], 0, v[2:3]
	v_or_b32_e32 v2, 0x50, v7
	v_lshl_add_u64 v[14:15], v[14:15], 0, v[152:153]
	v_mul_u32_u24_e32 v2, s34, v2
	s_waitcnt lgkmcnt(0)
	global_store_dwordx4 v[14:15], v[148:151], off
	ds_read_b128 v[14:17], v9 offset:11520
	v_lshlrev_b32_e32 v2, 1, v2
	v_lshl_add_u64 v[148:149], s[36:37], 0, v[2:3]
	v_lshl_add_u64 v[154:155], v[148:149], 0, v[152:153]
	ds_read_b128 v[148:151], v9 offset:12672
	v_or_b32_e32 v2, 0x58, v7
	v_mul_u32_u24_e32 v2, s34, v2
	v_lshlrev_b32_e32 v2, 1, v2
	s_waitcnt lgkmcnt(1)
	global_store_dwordx4 v[154:155], v[14:17], off
	s_nop 1
	v_lshl_add_u64 v[14:15], s[36:37], 0, v[2:3]
	v_or_b32_e32 v2, 0x60, v7
	v_lshl_add_u64 v[14:15], v[14:15], 0, v[152:153]
	v_mul_u32_u24_e32 v2, s34, v2
	s_waitcnt lgkmcnt(0)
	global_store_dwordx4 v[14:15], v[148:151], off
	ds_read_b128 v[14:17], v9 offset:13824
	v_lshlrev_b32_e32 v2, 1, v2
	v_lshl_add_u64 v[148:149], s[36:37], 0, v[2:3]
	v_lshl_add_u64 v[154:155], v[148:149], 0, v[152:153]
	ds_read_b128 v[148:151], v9 offset:14976
	v_or_b32_e32 v2, 0x68, v7
	v_mul_u32_u24_e32 v2, s34, v2
	v_lshlrev_b32_e32 v2, 1, v2
	s_waitcnt lgkmcnt(1)
	global_store_dwordx4 v[154:155], v[14:17], off
	s_nop 1
	v_lshl_add_u64 v[14:15], s[36:37], 0, v[2:3]
	v_or_b32_e32 v2, 0x70, v7
	v_lshl_add_u64 v[14:15], v[14:15], 0, v[152:153]
	v_mul_u32_u24_e32 v2, s34, v2
	s_waitcnt lgkmcnt(0)
	global_store_dwordx4 v[14:15], v[148:151], off
	ds_read_b128 v[14:17], v9 offset:16128
	v_lshlrev_b32_e32 v2, 1, v2
	v_lshl_add_u64 v[148:149], s[36:37], 0, v[2:3]
	v_lshl_add_u64 v[154:155], v[148:149], 0, v[152:153]
	ds_read_b128 v[148:151], v9 offset:17280
	v_or_b32_e32 v2, 0x78, v7
	v_mul_u32_u24_e32 v2, s34, v2
	v_lshlrev_b32_e32 v2, 1, v2
	s_waitcnt lgkmcnt(1)
	global_store_dwordx4 v[154:155], v[14:17], off
	s_nop 1
	v_lshl_add_u64 v[14:15], s[36:37], 0, v[2:3]
	v_lshl_add_u64 v[14:15], v[14:15], 0, v[152:153]
	s_waitcnt lgkmcnt(0)
	global_store_dwordx4 v[14:15], v[148:151], off

; __device__ __forceinline__ unsigned pk2(float lo, float hi) { f32x2_t v = {lo, hi}; bf16x2_t b = __builtin_convertvector(v, bf16x2_t); return __builtin_bit_cast(unsigned, b); }
; __device__ __forceinline__ float fsigmoid(float x) { return __builtin_amdgcn_rcpf(1.f + fexp(-x)); }
;     ...
;         for (int tt = 0; tt < 4; ++tt) {
;           u16* srow = stg + (tt * 32 + l31) * LD;
; #pragma unroll
;           for (int ct = 0; ct < 2; ++ct)
; #pragma unroll
;             for (int rq = 0; rq < 4; ++rq) {
;               float v[4];
; #pragma unroll
;               for (int e = 0; e < 4; ++e) { v[e] = acc[ct][tt][rq * 4 + e] * rsv[tt]; if (act) v[e] = v[e] * fsigmoid(v[e]); }
;               u32x2 w; w.x = pk2(v[0], v[1]); w.y = pk2(v[2], v[3]);
;               *(u32x2*)(srow + ct * 32 + 8 * rq + 4 * h) = w;
.Lp1_raw:
	s_add_u32 s38, s0, s38
	s_addc_u32 s39, s1, s39
	s_load_dwordx2 s[38:39], s[38:39], 0x0
	s_add_i32 s20, s35, s64
	v_mul_u32_u24_e32 v2, 0x90, v225
	v_add3_u32 v2, s7, v5, v2
	s_waitcnt vmcnt(3)
	v_pk_mul_f32 v[178:179], v[114:115], v[10:11] op_sel_hi:[1,0]
	v_pk_mul_f32 v[180:181], v[116:117], v[10:11] op_sel_hi:[1,0]
	v_cvt_pk_bf16_f32 v194, v178, v179
	v_cvt_pk_bf16_f32 v195, v180, v181
	ds_write_b64 v2, v[194:195] offset:0
	v_pk_mul_f32 v[182:183], v[118:119], v[10:11] op_sel_hi:[1,0]
	v_pk_mul_f32 v[184:185], v[120:121], v[10:11] op_sel_hi:[1,0]
	v_cvt_pk_bf16_f32 v196, v182, v183
	v_cvt_pk_bf16_f32 v197, v184, v185
	ds_write_b64 v2, v[196:197] offset:16
	v_pk_mul_f32 v[186:187], v[122:123], v[10:11] op_sel_hi:[1,0]
	v_pk_mul_f32 v[188:189], v[124:125], v[10:11] op_sel_hi:[1,0]
	v_cvt_pk_bf16_f32 v198, v186, v187
	v_cvt_pk_bf16_f32 v199, v188, v189
	ds_write_b64 v2, v[198:199] offset:32
	v_pk_mul_f32 v[190:191], v[126:127], v[10:11] op_sel_hi:[1,0]
	v_pk_mul_f32 v[192:193], v[128:129], v[10:11] op_sel_hi:[1,0]
	v_cvt_pk_bf16_f32 v200, v190, v191
	v_cvt_pk_bf16_f32 v201, v192, v193
	ds_write_b64 v2, v[200:201] offset:48
	v_pk_mul_f32 v[178:179], v[130:131], v[10:11] op_sel_hi:[1,0]
	v_pk_mul_f32 v[180:181], v[132:133], v[10:11] op_sel_hi:[1,0]
	v_cvt_pk_bf16_f32 v202, v178, v179
	v_cvt_pk_bf16_f32 v203, v180, v181
	ds_write_b64 v2, v[202:203] offset:64
	v_pk_mul_f32 v[182:183], v[134:135], v[10:11] op_sel_hi:[1,0]
	v_pk_mul_f32 v[184:185], v[136:137], v[10:11] op_sel_hi:[1,0]
	v_cvt_pk_bf16_f32 v204, v182, v183
	v_cvt_pk_bf16_f32 v205, v184, v185
	ds_write_b64 v2, v[204:205] offset:80
	v_pk_mul_f32 v[186:187], v[138:139], v[10:11] op_sel_hi:[1,0]
	v_pk_mul_f32 v[188:189], v[140:141], v[10:11] op_sel_hi:[1,0]
	v_cvt_pk_bf16_f32 v206, v186, v187
	v_cvt_pk_bf16_f32 v207, v188, v189
	ds_write_b64 v2, v[206:207] offset:96
	v_pk_mul_f32 v[190:191], v[142:143], v[10:11] op_sel_hi:[1,0]
	v_pk_mul_f32 v[192:193], v[144:145], v[10:11] op_sel_hi:[1,0]
	v_cvt_pk_bf16_f32 v208, v190, v191
	v_cvt_pk_bf16_f32 v209, v192, v193
	ds_write_b64 v2, v[208:209] offset:112
	s_waitcnt vmcnt(2)
	v_pk_mul_f32 v[178:179], v[82:83], v[8:9] op_sel_hi:[1,0]
	v_pk_mul_f32 v[180:181], v[84:85], v[8:9] op_sel_hi:[1,0]
	v_cvt_pk_bf16_f32 v194, v178, v179
	v_cvt_pk_bf16_f32 v195, v180, v181
	ds_write_b64 v2, v[194:195] offset:4608
	v_pk_mul_f32 v[182:183], v[86:87], v[8:9] op_sel_hi:[1,0]
	v_pk_mul_f32 v[184:185], v[88:89], v[8:9] op_sel_hi:[1,0]
	v_cvt_pk_bf16_f32 v196, v182, v183
	v_cvt_pk_bf16_f32 v197, v184, v185
	ds_write_b64 v2, v[196:197] offset:4624
	v_pk_mul_f32 v[186:187], v[90:91], v[8:9] op_sel_hi:[1,0]
	v_pk_mul_f32 v[188:189], v[92:93], v[8:9] op_sel_hi:[1,0]
	v_cvt_pk_bf16_f32 v198, v186, v187
	v_cvt_pk_bf16_f32 v199, v188, v189
	ds_write_b64 v2, v[198:199] offset:4640
	v_pk_mul_f32 v[190:191], v[94:95], v[8:9] op_sel_hi:[1,0]
	v_pk_mul_f32 v[192:193], v[96:97], v[8:9] op_sel_hi:[1,0]
	v_cvt_pk_bf16_f32 v200, v190, v191
	v_cvt_pk_bf16_f32 v201, v192, v193
	ds_write_b64 v2, v[200:201] offset:4656
	v_pk_mul_f32 v[178:179], v[98:99], v[8:9] op_sel_hi:[1,0]
	v_pk_mul_f32 v[180:181], v[100:101], v[8:9] op_sel_hi:[1,0]
	v_cvt_pk_bf16_f32 v202, v178, v179
	v_cvt_pk_bf16_f32 v203, v180, v181
	ds_write_b64 v2, v[202:203] offset:4672
	v_pk_mul_f32 v[182:183], v[102:103], v[8:9] op_sel_hi:[1,0]
	v_pk_mul_f32 v[184:185], v[104:105], v[8:9] op_sel_hi:[1,0]
	v_cvt_pk_bf16_f32 v204, v182, v183
	v_cvt_pk_bf16_f32 v205, v184, v185
	ds_write_b64 v2, v[204:205] offset:4688
	v_pk_mul_f32 v[186:187], v[106:107], v[8:9] op_sel_hi:[1,0]
	v_pk_mul_f32 v[188:189], v[108:109], v[8:9] op_sel_hi:[1,0]
	v_cvt_pk_bf16_f32 v206, v186, v187
	v_cvt_pk_bf16_f32 v207, v188, v189
	ds_write_b64 v2, v[206:207] offset:4704
	v_pk_mul_f32 v[190:191], v[110:111], v[8:9] op_sel_hi:[1,0]
	v_pk_mul_f32 v[192:193], v[112:113], v[8:9] op_sel_hi:[1,0]
	v_cvt_pk_bf16_f32 v208, v190, v191
	v_cvt_pk_bf16_f32 v209, v192, v193
	ds_write_b64 v2, v[208:209] offset:4720
	s_waitcnt vmcnt(1)
	v_pk_mul_f32 v[178:179], v[50:51], v[6:7] op_sel_hi:[1,0]
	v_pk_mul_f32 v[180:181], v[52:53], v[6:7] op_sel_hi:[1,0]
	v_cvt_pk_bf16_f32 v194, v178, v179
	v_cvt_pk_bf16_f32 v195, v180, v181
	ds_write_b64 v2, v[194:195] offset:9216
	v_pk_mul_f32 v[182:183], v[54:55], v[6:7] op_sel_hi:[1,0]
	v_pk_mul_f32 v[184:185], v[56:57], v[6:7] op_sel_hi:[1,0]
	v_cvt_pk_bf16_f32 v196, v182, v183
	v_cvt_pk_bf16_f32 v197, v184, v185
	ds_write_b64 v2, v[196:197] offset:9232
	v_pk_mul_f32 v[186:187], v[58:59], v[6:7] op_sel_hi:[1,0]
	v_pk_mul_f32 v[188:189], v[60:61], v[6:7] op_sel_hi:[1,0]
	v_cvt_pk_bf16_f32 v198, v186, v187
	v_cvt_pk_bf16_f32 v199, v188, v189
	ds_write_b64 v2, v[198:199] offset:9248
	v_pk_mul_f32 v[190:191], v[62:63], v[6:7] op_sel_hi:[1,0]
	v_pk_mul_f32 v[192:193], v[64:65], v[6:7] op_sel_hi:[1,0]
	v_cvt_pk_bf16_f32 v200, v190, v191
	v_cvt_pk_bf16_f32 v201, v192, v193
	ds_write_b64 v2, v[200:201] offset:9264
	v_pk_mul_f32 v[178:179], v[66:67], v[6:7] op_sel_hi:[1,0]
	v_pk_mul_f32 v[180:181], v[68:69], v[6:7] op_sel_hi:[1,0]
	v_cvt_pk_bf16_f32 v202, v178, v179
	v_cvt_pk_bf16_f32 v203, v180, v181
	ds_write_b64 v2, v[202:203] offset:9280
	v_pk_mul_f32 v[182:183], v[70:71], v[6:7] op_sel_hi:[1,0]
	v_pk_mul_f32 v[184:185], v[72:73], v[6:7] op_sel_hi:[1,0]
	v_cvt_pk_bf16_f32 v204, v182, v183
	v_cvt_pk_bf16_f32 v205, v184, v185
	ds_write_b64 v2, v[204:205] offset:9296
	v_pk_mul_f32 v[186:187], v[74:75], v[6:7] op_sel_hi:[1,0]
	v_pk_mul_f32 v[188:189], v[76:77], v[6:7] op_sel_hi:[1,0]
	v_cvt_pk_bf16_f32 v206, v186, v187
	v_cvt_pk_bf16_f32 v207, v188, v189
	ds_write_b64 v2, v[206:207] offset:9312
	v_pk_mul_f32 v[190:191], v[78:79], v[6:7] op_sel_hi:[1,0]
	v_pk_mul_f32 v[192:193], v[80:81], v[6:7] op_sel_hi:[1,0]
	v_cvt_pk_bf16_f32 v208, v190, v191
	v_cvt_pk_bf16_f32 v209, v192, v193
	ds_write_b64 v2, v[208:209] offset:9328
	s_waitcnt vmcnt(0)
; __device__ __forceinline__ unsigned pk2(float lo, float hi) { f32x2_t v = {lo, hi}; bf16x2_t b = __builtin_convertvector(v, bf16x2_t); return __builtin_bit_cast(unsigned, b); }
; __device__ __forceinline__ float fsigmoid(float x) { return __builtin_amdgcn_rcpf(1.f + fexp(-x)); }
;     ...
;       auto flush_rows = [&](u16* gbase, size_t ldd) {
; #pragma unroll
;         for (int it = 0; it < 16; ++it) {
;           const int r = it * 8 + (lane >> 3), ch = lane & 7;
;           *(u32x4*)(gbase + (size_t)r * ldd + ch * 8) = *(const u32x4*)(stg + r * LD + ch * 8);
;         }
;       };
;     ...
;         for (int tt = 0; tt < 4; ++tt) {
;           u16* srow = stg + (tt * 32 + l31) * LD;
; #pragma unroll
;           for (int ct = 0; ct < 2; ++ct)
; #pragma unroll
;             for (int rq = 0; rq < 4; ++rq) {
;               float v[4];
; #pragma unroll
;               for (int e = 0; e < 4; ++e) { v[e] = acc[ct][tt][rq * 4 + e] * rsv[tt]; if (act) v[e] = v[e] * fsigmoid(v[e]); }
;               u32x2 w; w.x = pk2(v[0], v[1]); w.y = pk2(v[2], v[3]);
;               *(u32x2*)(srow + ct * 32 + 8 * rq + 4 * h) = w;
;             }
;         }
;         flush_rows(dst + (size_t)(m0 + wr * 128) * ldd + c0, (size_t)ldd);
	v_pk_mul_f32 v[178:179], v[18:19], v[4:5] op_sel_hi:[1,0]
	v_pk_mul_f32 v[180:181], v[20:21], v[4:5] op_sel_hi:[1,0]
	v_cvt_pk_bf16_f32 v194, v178, v179
	v_cvt_pk_bf16_f32 v195, v180, v181
	ds_write_b64 v2, v[194:195] offset:13824
	v_pk_mul_f32 v[182:183], v[22:23], v[4:5] op_sel_hi:[1,0]
	v_pk_mul_f32 v[184:185], v[24:25], v[4:5] op_sel_hi:[1,0]
	v_cvt_pk_bf16_f32 v196, v182, v183
	v_cvt_pk_bf16_f32 v197, v184, v185
	ds_write_b64 v2, v[196:197] offset:13840
	v_pk_mul_f32 v[186:187], v[26:27], v[4:5] op_sel_hi:[1,0]
	v_pk_mul_f32 v[188:189], v[28:29], v[4:5] op_sel_hi:[1,0]
	v_cvt_pk_bf16_f32 v198, v186, v187
	v_cvt_pk_bf16_f32 v199, v188, v189
	ds_write_b64 v2, v[198:199] offset:13856
	v_pk_mul_f32 v[190:191], v[30:31], v[4:5] op_sel_hi:[1,0]
	v_pk_mul_f32 v[192:193], v[32:33], v[4:5] op_sel_hi:[1,0]
	v_cvt_pk_bf16_f32 v200, v190, v191
	v_cvt_pk_bf16_f32 v201, v192, v193
	ds_write_b64 v2, v[200:201] offset:13872
	v_pk_mul_f32 v[178:179], v[34:35], v[4:5] op_sel_hi:[1,0]
	v_pk_mul_f32 v[180:181], v[36:37], v[4:5] op_sel_hi:[1,0]
	v_cvt_pk_bf16_f32 v202, v178, v179
	v_cvt_pk_bf16_f32 v203, v180, v181
	ds_write_b64 v2, v[202:203] offset:13888
	v_pk_mul_f32 v[182:183], v[38:39], v[4:5] op_sel_hi:[1,0]
	v_pk_mul_f32 v[184:185], v[40:41], v[4:5] op_sel_hi:[1,0]
	v_cvt_pk_bf16_f32 v204, v182, v183
	v_cvt_pk_bf16_f32 v205, v184, v185
	ds_write_b64 v2, v[204:205] offset:13904
	v_pk_mul_f32 v[186:187], v[42:43], v[4:5] op_sel_hi:[1,0]
	v_pk_mul_f32 v[188:189], v[44:45], v[4:5] op_sel_hi:[1,0]
	v_cvt_pk_bf16_f32 v206, v186, v187
	v_cvt_pk_bf16_f32 v207, v188, v189
	ds_write_b64 v2, v[206:207] offset:13920
	v_pk_mul_f32 v[190:191], v[46:47], v[4:5] op_sel_hi:[1,0]
	v_pk_mul_f32 v[192:193], v[48:49], v[4:5] op_sel_hi:[1,0]
	v_cvt_pk_bf16_f32 v208, v190, v191
	v_cvt_pk_bf16_f32 v209, v192, v193
	ds_write_b64 v2, v[208:209] offset:13936
	v_lshrrev_b32_e32 v7, 3, v147
	v_lshlrev_b32_e32 v9, 4, v225
	v_and_b32_e32 v9, 0x70, v9
	v_mul_u32_u24_e32 v11, 0x90, v7
	v_add3_u32 v11, s7, v11, v9
	v_mul_u32_u24_e32 v13, s34, v7
	v_lshl_add_u32 v13, v13, 1, v9
	s_mul_i32 s36, s34, s31
	s_add_i32 s36, s36, s20
	s_lshl_b32 s36, s36, 1
	s_lshl_b32 s31, s34, 4
	s_waitcnt lgkmcnt(0)
	s_add_u32 s36, s38, s36
	s_addc_u32 s37, s39, 0
	ds_read_b128 v[178:181], v11
	ds_read_b128 v[182:185], v11 offset:1152
	ds_read_b128 v[186:189], v11 offset:2304
	ds_read_b128 v[190:193], v11 offset:3456
	s_waitcnt lgkmcnt(3)
	global_store_dwordx4 v13, v[178:181], s[36:37]
	s_add_u32 s36, s36, s31
	s_addc_u32 s37, s37, 0
	ds_read_b128 v[178:181], v11 offset:4608
	s_waitcnt lgkmcnt(3)
	global_store_dwordx4 v13, v[182:185], s[36:37]
	s_add_u32 s36, s36, s31
	s_addc_u32 s37, s37, 0
	ds_read_b128 v[182:185], v11 offset:5760
	s_waitcnt lgkmcnt(3)
	global_store_dwordx4 v13, v[186:189], s[36:37]
	s_add_u32 s36, s36, s31
	s_addc_u32 s37, s37, 0
	ds_read_b128 v[186:189], v11 offset:6912
	s_waitcnt lgkmcnt(3)
	global_store_dwordx4 v13, v[190:193], s[36:37]
	s_add_u32 s36, s36, s31
	s_addc_u32 s37, s37, 0
	ds_read_b128 v[190:193], v11 offset:8064
	s_waitcnt lgkmcnt(3)
	global_store_dwordx4 v13, v[178:181], s[36:37]
	s_add_u32 s36, s36, s31
	s_addc_u32 s37, s37, 0
	ds_read_b128 v[178:181], v11 offset:9216
	s_waitcnt lgkmcnt(3)
	global_store_dwordx4 v13, v[182:185], s[36:37]
	s_add_u32 s36, s36, s31
	s_addc_u32 s37, s37, 0
	ds_read_b128 v[182:185], v11 offset:10368
	s_waitcnt lgkmcnt(3)
	global_store_dwordx4 v13, v[186:189], s[36:37]
	s_add_u32 s36, s36, s31
	s_addc_u32 s37, s37, 0
	ds_read_b128 v[186:189], v11 offset:11520
	s_waitcnt lgkmcnt(3)
	global_store_dwordx4 v13, v[190:193], s[36:37]
	s_add_u32 s36, s36, s31
	s_addc_u32 s37, s37, 0
	ds_read_b128 v[190:193], v11 offset:12672
	s_waitcnt lgkmcnt(3)
	global_store_dwordx4 v13, v[178:181], s[36:37]
	s_add_u32 s36, s36, s31
	s_addc_u32 s37, s37, 0
	ds_read_b128 v[178:181], v11 offset:13824
	s_waitcnt lgkmcnt(3)
	global_store_dwordx4 v13, v[182:185], s[36:37]
	s_add_u32 s36, s36, s31
	s_addc_u32 s37, s37, 0
	ds_read_b128 v[182:185], v11 offset:14976
	s_waitcnt lgkmcnt(3)
	global_store_dwordx4 v13, v[186:189], s[36:37]
	s_add_u32 s36, s36, s31
	s_addc_u32 s37, s37, 0
	ds_read_b128 v[186:189], v11 offset:16128
	s_waitcnt lgkmcnt(3)
	global_store_dwordx4 v13, v[190:193], s[36:37]
	s_add_u32 s36, s36, s31
	s_addc_u32 s37, s37, 0
	ds_read_b128 v[190:193], v11 offset:17280
	s_waitcnt lgkmcnt(3)
	global_store_dwordx4 v13, v[178:181], s[36:37]
	s_add_u32 s36, s36, s31
	s_addc_u32 s37, s37, 0
	s_waitcnt lgkmcnt(2)
	global_store_dwordx4 v13, v[182:185], s[36:37]
	s_add_u32 s36, s36, s31
	s_addc_u32 s37, s37, 0
	s_waitcnt lgkmcnt(1)
	global_store_dwordx4 v13, v[186:189], s[36:37]
	s_add_u32 s36, s36, s31
	s_addc_u32 s37, s37, 0
	s_waitcnt lgkmcnt(0)
	global_store_dwordx4 v13, v[190:193], s[36:37]
	s_add_u32 s36, s36, s31
	s_addc_u32 s37, s37, 0
	s_branch .LBB0_102
